# v18 + scan: previous-chunk y convert/store deferred past the first step's LDS wait (no exposed ds_read latency in the loop header)
# speedup vs baseline: 1.0125x; 1.0029x over previous
; #define PG8_LAS __attribute__((address_space(3)))
; __device__ __forceinline__ bf16_t f2bf(float f) { unsigned u = __float_as_uint(f); u += 0x7FFFu + ((u >> 16) & 1u); return (bf16_t)(u >> 16); }
; #define RW_WAIT(P, N) asm volatile("s_waitcnt lgkmcnt(" #N ")" : "+v"(P##w4), "+v"(P##kk4), "+v"(P##wr4), "+v"(P##ka4), "+v"(P##kp4), "+v"(P##v), "+v"(P##cc))
; #define RW_PAIR(ST) do { RW_LOAD(B, (ST) + 1); RW_WAIT(A, 7); RW_STEP(A, ST); RW_LOAD(A, (ST) + 2); RW_WAIT(B, 7); RW_STEP(B, (ST) + 1); } while (0)
; __device__ __forceinline__ void scans(int l, int s, unsigned char* shm) {
;     ...
;         for (int cidx = 0; cidx < NCH; ++cidx) {
;             if (cidx > 0) { const int st = tid >> 4, r = tid & 15; Y[(size_t)(b_r * 2048 + (cidx - 1) * CS + st) * 512 + h_r * 64 + rbase + r] = f2bf(yl[((cidx - 1) & 1) * (CS * 16) + tid]); }
;             const float* bp = rbuf + (cidx & 1) * (CS * RST); float* ylw = yl + (cidx & 1) * (CS * 16);
;             const unsigned ab = (unsigned)(size_t)(PG8_LAS const float*)bp;
;             const unsigned a_col = ab + col4 * 4, a_row = ab + 1280 + loc * 4, a_cc = ab + 1344;
;             f32x4 Aw4, Akk4, Awr4, Aka4, Akp4, Bw4, Bkk4, Bwr4, Bka4, Bkp4; float Av, Bv; f32x2 Acc, Bcc;
;             float ykeep = 0.f;
;     ...
;             RW_LOAD(A, 0);
;             RW_PAIR(0); RW_PAIR(2); RW_PAIR(4); RW_PAIR(6); RW_PAIR(8); RW_PAIR(10); RW_PAIR(12);
;             RW_LOAD(B, 15); RW_WAIT(A, 7); RW_STEP(A, 14); RW_WAIT(B, 0); RW_STEP(B, 15);
.LBB0_758:
	s_and_b32 s20, s16, 1
	s_mul_i32 s21, s20, 0x5500
	v_add_u32_e32 v11, s21, v176
	v_add_u32_e32 v15, s21, v13
	s_addk_i32 s21, 0x540
	v_mov_b32_e32 v16, s21
	ds_read_b128 v[20:23], v11
	ds_read_b128 v[24:27], v11 offset:256
	ds_read_b128 v[28:31], v11 offset:512
	ds_read_b128 v[32:35], v11 offset:768
	ds_read_b128 v[36:39], v11 offset:1024
	ds_read_b32 v40, v15
	ds_read_b128 v[44:47], v11 offset:1360
	ds_read_b128 v[48:51], v11 offset:1616
	ds_read_b128 v[52:55], v11 offset:1872
	ds_read_b128 v[56:59], v11 offset:2128
	ds_read_b128 v[60:63], v11 offset:2384
	s_waitcnt lgkmcnt(5)
	s_cmp_eq_u32 s16, 0
	s_cbranch_scc1 .Lscan_noy
	v_bfe_u32 v122, v119, 16, 1
	v_add3_u32 v122, v119, v122, s78
	global_store_short_d16_hi v[120:121], v122, off
.Lscan_noy:
	v_pk_mul_f32 v[84:85], v[0:1], v[24:25]
	v_pk_fma_f32 v[84:85], v[2:3], v[26:27], v[84:85]
	v_add_f32_e32 v86, v84, v85
	v_pk_mul_f32 v[90:91], v[0:1], v[28:29]
	v_pk_fma_f32 v[90:91], v[2:3], v[30:31], v[90:91]
	v_add_f32_dpp v88, v86, v86 quad_perm:[1,0,3,2] row_mask:0xf bank_mask:0xf bound_ctrl:1
	v_pk_mul_f32 v[92:93], v[36:37], v[40:41] op_sel_hi:[1,0]
	v_pk_fma_f32 v[92:93], v[0:1], v[20:21], v[92:93]
	v_add_f32_dpp v88, v88, v88 quad_perm:[2,3,0,1] row_mask:0xf bank_mask:0xf bound_ctrl:1
	v_pk_mul_f32 v[94:95], v[38:39], v[40:41] op_sel_hi:[1,0]
	v_pk_fma_f32 v[94:95], v[2:3], v[22:23], v[94:95]
	v_add_f32_dpp v88, v88, v88 row_half_mirror row_mask:0xf bank_mask:0xf bound_ctrl:1
	v_add_f32_e32 v68, v90, v91
	ds_read_b32 v64, v15 offset:1360
	v_add_f32_dpp v88, v88, v88 row_mirror row_mask:0xf bank_mask:0xf bound_ctrl:1
	v_pk_fma_f32 v[0:1], v[32:33], v[88:89], v[92:93] op_sel_hi:[1,0,1] neg_lo:[0,1,0] neg_hi:[0,1,0]
	v_pk_fma_f32 v[2:3], v[34:35], v[88:89], v[94:95] op_sel_hi:[1,0,1] neg_lo:[0,1,0] neg_hi:[0,1,0]
	v_mov_b32_e32 v114, v88
	ds_read_b128 v[20:23], v11 offset:2720
	ds_read_b128 v[24:27], v11 offset:2976
	ds_read_b128 v[28:31], v11 offset:3232
	ds_read_b128 v[32:35], v11 offset:3488
	ds_read_b128 v[36:39], v11 offset:3744
	s_waitcnt lgkmcnt(5)
	v_pk_mul_f32 v[84:85], v[0:1], v[48:49]
	v_pk_fma_f32 v[84:85], v[2:3], v[50:51], v[84:85]
	v_add_f32_e32 v86, v84, v85
	v_pk_mul_f32 v[90:91], v[0:1], v[52:53]
	v_pk_fma_f32 v[90:91], v[2:3], v[54:55], v[90:91]
	v_add_f32_dpp v88, v86, v86 quad_perm:[1,0,3,2] row_mask:0xf bank_mask:0xf bound_ctrl:1
	v_pk_mul_f32 v[92:93], v[60:61], v[64:65] op_sel_hi:[1,0]
	v_pk_fma_f32 v[92:93], v[0:1], v[44:45], v[92:93]
	v_add_f32_dpp v88, v88, v88 quad_perm:[2,3,0,1] row_mask:0xf bank_mask:0xf bound_ctrl:1
	v_pk_mul_f32 v[94:95], v[62:63], v[64:65] op_sel_hi:[1,0]
	v_pk_fma_f32 v[94:95], v[2:3], v[46:47], v[94:95]
	v_add_f32_dpp v88, v88, v88 row_half_mirror row_mask:0xf bank_mask:0xf bound_ctrl:1
	v_add_f32_e32 v69, v90, v91
	ds_read_b32 v40, v15 offset:2720
	v_add_f32_dpp v88, v88, v88 row_mirror row_mask:0xf bank_mask:0xf bound_ctrl:1
	v_pk_fma_f32 v[0:1], v[56:57], v[88:89], v[92:93] op_sel_hi:[1,0,1] neg_lo:[0,1,0] neg_hi:[0,1,0]
	v_pk_fma_f32 v[2:3], v[58:59], v[88:89], v[94:95] op_sel_hi:[1,0,1] neg_lo:[0,1,0] neg_hi:[0,1,0]
	v_cndmask_b32_e64 v114, v114, v88, s[40:41]
	ds_read_b128 v[44:47], v11 offset:4080
	ds_read_b128 v[48:51], v11 offset:4336
	ds_read_b128 v[52:55], v11 offset:4592
	ds_read_b128 v[56:59], v11 offset:4848
	ds_read_b128 v[60:63], v11 offset:5104
	s_waitcnt lgkmcnt(5)
	v_pk_mul_f32 v[84:85], v[0:1], v[24:25]
	v_pk_fma_f32 v[84:85], v[2:3], v[26:27], v[84:85]
	v_add_f32_e32 v86, v84, v85
	v_pk_mul_f32 v[90:91], v[0:1], v[28:29]
	v_pk_fma_f32 v[90:91], v[2:3], v[30:31], v[90:91]
	v_add_f32_dpp v88, v86, v86 quad_perm:[1,0,3,2] row_mask:0xf bank_mask:0xf bound_ctrl:1
	v_pk_mul_f32 v[92:93], v[36:37], v[40:41] op_sel_hi:[1,0]
	v_pk_fma_f32 v[92:93], v[0:1], v[20:21], v[92:93]
	v_add_f32_dpp v88, v88, v88 quad_perm:[2,3,0,1] row_mask:0xf bank_mask:0xf bound_ctrl:1
	v_pk_mul_f32 v[94:95], v[38:39], v[40:41] op_sel_hi:[1,0]
	v_pk_fma_f32 v[94:95], v[2:3], v[22:23], v[94:95]
	v_add_f32_dpp v88, v88, v88 row_half_mirror row_mask:0xf bank_mask:0xf bound_ctrl:1
	v_add_f32_e32 v70, v90, v91
	ds_read_b32 v64, v15 offset:4080
	v_add_f32_dpp v88, v88, v88 row_mirror row_mask:0xf bank_mask:0xf bound_ctrl:1
	v_pk_fma_f32 v[0:1], v[32:33], v[88:89], v[92:93] op_sel_hi:[1,0,1] neg_lo:[0,1,0] neg_hi:[0,1,0]
	v_pk_fma_f32 v[2:3], v[34:35], v[88:89], v[94:95] op_sel_hi:[1,0,1] neg_lo:[0,1,0] neg_hi:[0,1,0]
	v_cndmask_b32_e64 v114, v114, v88, s[42:43]
	ds_read_b128 v[20:23], v11 offset:5440
	ds_read_b128 v[24:27], v11 offset:5696
	ds_read_b128 v[28:31], v11 offset:5952
	ds_read_b128 v[32:35], v11 offset:6208
	ds_read_b128 v[36:39], v11 offset:6464
	s_waitcnt lgkmcnt(5)
	v_pk_mul_f32 v[84:85], v[0:1], v[48:49]
	v_pk_fma_f32 v[84:85], v[2:3], v[50:51], v[84:85]
	v_add_f32_e32 v86, v84, v85
	v_pk_mul_f32 v[90:91], v[0:1], v[52:53]
	v_pk_fma_f32 v[90:91], v[2:3], v[54:55], v[90:91]
	v_add_f32_dpp v88, v86, v86 quad_perm:[1,0,3,2] row_mask:0xf bank_mask:0xf bound_ctrl:1
	v_pk_mul_f32 v[92:93], v[60:61], v[64:65] op_sel_hi:[1,0]
	v_pk_fma_f32 v[92:93], v[0:1], v[44:45], v[92:93]
	v_add_f32_dpp v88, v88, v88 quad_perm:[2,3,0,1] row_mask:0xf bank_mask:0xf bound_ctrl:1
	v_pk_mul_f32 v[94:95], v[62:63], v[64:65] op_sel_hi:[1,0]
	v_pk_fma_f32 v[94:95], v[2:3], v[46:47], v[94:95]
	v_add_f32_dpp v88, v88, v88 row_half_mirror row_mask:0xf bank_mask:0xf bound_ctrl:1
	v_add_f32_e32 v71, v90, v91
	ds_read_b32 v40, v15 offset:5440
	v_add_f32_dpp v88, v88, v88 row_mirror row_mask:0xf bank_mask:0xf bound_ctrl:1
	v_pk_fma_f32 v[0:1], v[56:57], v[88:89], v[92:93] op_sel_hi:[1,0,1] neg_lo:[0,1,0] neg_hi:[0,1,0]
	v_pk_fma_f32 v[2:3], v[58:59], v[88:89], v[94:95] op_sel_hi:[1,0,1] neg_lo:[0,1,0] neg_hi:[0,1,0]
	v_cndmask_b32_e64 v114, v114, v88, s[44:45]
	ds_read_b128 v[44:47], v11 offset:6800
	ds_read_b128 v[48:51], v11 offset:7056
	ds_read_b128 v[52:55], v11 offset:7312
	ds_read_b128 v[56:59], v11 offset:7568
	ds_read_b128 v[60:63], v11 offset:7824
	s_waitcnt lgkmcnt(5)
; #define RW_PAIR(ST) do { RW_LOAD(B, (ST) + 1); RW_WAIT(A, 7); RW_STEP(A, ST); RW_LOAD(A, (ST) + 2); RW_WAIT(B, 7); RW_STEP(B, (ST) + 1); } while (0)
; __device__ __forceinline__ void scans(int l, int s, unsigned char* shm) {
;     ...
;             RW_LOAD(A, 0);
;             RW_PAIR(0); RW_PAIR(2); RW_PAIR(4); RW_PAIR(6); RW_PAIR(8); RW_PAIR(10); RW_PAIR(12);
	v_pk_mul_f32 v[84:85], v[0:1], v[24:25]
	v_pk_fma_f32 v[84:85], v[2:3], v[26:27], v[84:85]
	v_add_f32_e32 v86, v84, v85
	v_pk_mul_f32 v[90:91], v[0:1], v[28:29]
	v_pk_fma_f32 v[90:91], v[2:3], v[30:31], v[90:91]
	v_add_f32_dpp v88, v86, v86 quad_perm:[1,0,3,2] row_mask:0xf bank_mask:0xf bound_ctrl:1
	v_pk_mul_f32 v[92:93], v[36:37], v[40:41] op_sel_hi:[1,0]
	v_pk_fma_f32 v[92:93], v[0:1], v[20:21], v[92:93]
	v_add_f32_dpp v88, v88, v88 quad_perm:[2,3,0,1] row_mask:0xf bank_mask:0xf bound_ctrl:1
	v_pk_mul_f32 v[94:95], v[38:39], v[40:41] op_sel_hi:[1,0]
	v_pk_fma_f32 v[94:95], v[2:3], v[22:23], v[94:95]
	v_add_f32_dpp v88, v88, v88 row_half_mirror row_mask:0xf bank_mask:0xf bound_ctrl:1
	v_add_f32_e32 v72, v90, v91
	ds_read_b32 v64, v15 offset:6800
	v_add_f32_dpp v88, v88, v88 row_mirror row_mask:0xf bank_mask:0xf bound_ctrl:1
	v_pk_fma_f32 v[0:1], v[32:33], v[88:89], v[92:93] op_sel_hi:[1,0,1] neg_lo:[0,1,0] neg_hi:[0,1,0]
	v_pk_fma_f32 v[2:3], v[34:35], v[88:89], v[94:95] op_sel_hi:[1,0,1] neg_lo:[0,1,0] neg_hi:[0,1,0]
	v_cndmask_b32_e64 v114, v114, v88, s[46:47]
	ds_read_b128 v[20:23], v11 offset:8160
	ds_read_b128 v[24:27], v11 offset:8416
	ds_read_b128 v[28:31], v11 offset:8672
	ds_read_b128 v[32:35], v11 offset:8928
	ds_read_b128 v[36:39], v11 offset:9184
	s_waitcnt lgkmcnt(5)
	v_pk_mul_f32 v[84:85], v[0:1], v[48:49]
	v_pk_fma_f32 v[84:85], v[2:3], v[50:51], v[84:85]
	v_add_f32_e32 v86, v84, v85
	v_pk_mul_f32 v[90:91], v[0:1], v[52:53]
	v_pk_fma_f32 v[90:91], v[2:3], v[54:55], v[90:91]
	v_add_f32_dpp v88, v86, v86 quad_perm:[1,0,3,2] row_mask:0xf bank_mask:0xf bound_ctrl:1
	v_pk_mul_f32 v[92:93], v[60:61], v[64:65] op_sel_hi:[1,0]
	v_pk_fma_f32 v[92:93], v[0:1], v[44:45], v[92:93]
	v_add_f32_dpp v88, v88, v88 quad_perm:[2,3,0,1] row_mask:0xf bank_mask:0xf bound_ctrl:1
	v_pk_mul_f32 v[94:95], v[62:63], v[64:65] op_sel_hi:[1,0]
	v_pk_fma_f32 v[94:95], v[2:3], v[46:47], v[94:95]
	v_add_f32_dpp v88, v88, v88 row_half_mirror row_mask:0xf bank_mask:0xf bound_ctrl:1
	v_add_f32_e32 v73, v90, v91
	ds_read_b32 v40, v15 offset:8160
	v_add_f32_dpp v88, v88, v88 row_mirror row_mask:0xf bank_mask:0xf bound_ctrl:1
	v_pk_fma_f32 v[0:1], v[56:57], v[88:89], v[92:93] op_sel_hi:[1,0,1] neg_lo:[0,1,0] neg_hi:[0,1,0]
	v_pk_fma_f32 v[2:3], v[58:59], v[88:89], v[94:95] op_sel_hi:[1,0,1] neg_lo:[0,1,0] neg_hi:[0,1,0]
	v_cndmask_b32_e64 v114, v114, v88, s[48:49]
	ds_read_b128 v[44:47], v11 offset:9520
	ds_read_b128 v[48:51], v11 offset:9776
	ds_read_b128 v[52:55], v11 offset:10032
	ds_read_b128 v[56:59], v11 offset:10288
	ds_read_b128 v[60:63], v11 offset:10544
	s_waitcnt lgkmcnt(5)
	v_pk_mul_f32 v[84:85], v[0:1], v[24:25]
	v_pk_fma_f32 v[84:85], v[2:3], v[26:27], v[84:85]
	v_add_f32_e32 v86, v84, v85
	v_pk_mul_f32 v[90:91], v[0:1], v[28:29]
	v_pk_fma_f32 v[90:91], v[2:3], v[30:31], v[90:91]
	v_add_f32_dpp v88, v86, v86 quad_perm:[1,0,3,2] row_mask:0xf bank_mask:0xf bound_ctrl:1
	v_pk_mul_f32 v[92:93], v[36:37], v[40:41] op_sel_hi:[1,0]
	v_pk_fma_f32 v[92:93], v[0:1], v[20:21], v[92:93]
	v_add_f32_dpp v88, v88, v88 quad_perm:[2,3,0,1] row_mask:0xf bank_mask:0xf bound_ctrl:1
	v_pk_mul_f32 v[94:95], v[38:39], v[40:41] op_sel_hi:[1,0]
	v_pk_fma_f32 v[94:95], v[2:3], v[22:23], v[94:95]
	v_add_f32_dpp v88, v88, v88 row_half_mirror row_mask:0xf bank_mask:0xf bound_ctrl:1
	v_add_f32_e32 v74, v90, v91
	ds_read_b32 v64, v15 offset:9520
	v_add_f32_dpp v88, v88, v88 row_mirror row_mask:0xf bank_mask:0xf bound_ctrl:1
	v_pk_fma_f32 v[0:1], v[32:33], v[88:89], v[92:93] op_sel_hi:[1,0,1] neg_lo:[0,1,0] neg_hi:[0,1,0]
	v_pk_fma_f32 v[2:3], v[34:35], v[88:89], v[94:95] op_sel_hi:[1,0,1] neg_lo:[0,1,0] neg_hi:[0,1,0]
	v_cndmask_b32_e64 v114, v114, v88, s[50:51]
	ds_read_b128 v[20:23], v11 offset:10880
	ds_read_b128 v[24:27], v11 offset:11136
	ds_read_b128 v[28:31], v11 offset:11392
	ds_read_b128 v[32:35], v11 offset:11648
	ds_read_b128 v[36:39], v11 offset:11904
	s_waitcnt lgkmcnt(5)
	v_pk_mul_f32 v[84:85], v[0:1], v[48:49]
	v_pk_fma_f32 v[84:85], v[2:3], v[50:51], v[84:85]
	v_add_f32_e32 v86, v84, v85
	v_pk_mul_f32 v[90:91], v[0:1], v[52:53]
	v_pk_fma_f32 v[90:91], v[2:3], v[54:55], v[90:91]
	v_add_f32_dpp v88, v86, v86 quad_perm:[1,0,3,2] row_mask:0xf bank_mask:0xf bound_ctrl:1
	v_pk_mul_f32 v[92:93], v[60:61], v[64:65] op_sel_hi:[1,0]
	v_pk_fma_f32 v[92:93], v[0:1], v[44:45], v[92:93]
	v_add_f32_dpp v88, v88, v88 quad_perm:[2,3,0,1] row_mask:0xf bank_mask:0xf bound_ctrl:1
	v_pk_mul_f32 v[94:95], v[62:63], v[64:65] op_sel_hi:[1,0]
	v_pk_fma_f32 v[94:95], v[2:3], v[46:47], v[94:95]
	v_add_f32_dpp v88, v88, v88 row_half_mirror row_mask:0xf bank_mask:0xf bound_ctrl:1
	v_add_f32_e32 v75, v90, v91
	ds_read_b32 v40, v15 offset:10880
	v_add_f32_dpp v88, v88, v88 row_mirror row_mask:0xf bank_mask:0xf bound_ctrl:1
	v_pk_fma_f32 v[0:1], v[56:57], v[88:89], v[92:93] op_sel_hi:[1,0,1] neg_lo:[0,1,0] neg_hi:[0,1,0]
	v_pk_fma_f32 v[2:3], v[58:59], v[88:89], v[94:95] op_sel_hi:[1,0,1] neg_lo:[0,1,0] neg_hi:[0,1,0]
	v_cndmask_b32_e64 v114, v114, v88, s[52:53]
	ds_read_b128 v[44:47], v11 offset:12240
	ds_read_b128 v[48:51], v11 offset:12496
	ds_read_b128 v[52:55], v11 offset:12752
	ds_read_b128 v[56:59], v11 offset:13008
	ds_read_b128 v[60:63], v11 offset:13264
	s_waitcnt lgkmcnt(5)
; #define RW_PAIR(ST) do { RW_LOAD(B, (ST) + 1); RW_WAIT(A, 7); RW_STEP(A, ST); RW_LOAD(A, (ST) + 2); RW_WAIT(B, 7); RW_STEP(B, (ST) + 1); } while (0)
; __device__ __forceinline__ void scans(int l, int s, unsigned char* shm) {
;     ...
;             RW_LOAD(A, 0);
;             RW_PAIR(0); RW_PAIR(2); RW_PAIR(4); RW_PAIR(6); RW_PAIR(8); RW_PAIR(10); RW_PAIR(12);
	v_pk_mul_f32 v[84:85], v[0:1], v[24:25]
	v_pk_fma_f32 v[84:85], v[2:3], v[26:27], v[84:85]
	v_add_f32_e32 v86, v84, v85
	v_pk_mul_f32 v[90:91], v[0:1], v[28:29]
	v_pk_fma_f32 v[90:91], v[2:3], v[30:31], v[90:91]
	v_add_f32_dpp v88, v86, v86 quad_perm:[1,0,3,2] row_mask:0xf bank_mask:0xf bound_ctrl:1
	v_pk_mul_f32 v[92:93], v[36:37], v[40:41] op_sel_hi:[1,0]
	v_pk_fma_f32 v[92:93], v[0:1], v[20:21], v[92:93]
	v_add_f32_dpp v88, v88, v88 quad_perm:[2,3,0,1] row_mask:0xf bank_mask:0xf bound_ctrl:1
	v_pk_mul_f32 v[94:95], v[38:39], v[40:41] op_sel_hi:[1,0]
	v_pk_fma_f32 v[94:95], v[2:3], v[22:23], v[94:95]
	v_add_f32_dpp v88, v88, v88 row_half_mirror row_mask:0xf bank_mask:0xf bound_ctrl:1
	v_add_f32_e32 v76, v90, v91
	ds_read_b32 v64, v15 offset:12240
	v_add_f32_dpp v88, v88, v88 row_mirror row_mask:0xf bank_mask:0xf bound_ctrl:1
	v_pk_fma_f32 v[0:1], v[32:33], v[88:89], v[92:93] op_sel_hi:[1,0,1] neg_lo:[0,1,0] neg_hi:[0,1,0]
	v_pk_fma_f32 v[2:3], v[34:35], v[88:89], v[94:95] op_sel_hi:[1,0,1] neg_lo:[0,1,0] neg_hi:[0,1,0]
	v_cndmask_b32_e64 v114, v114, v88, s[54:55]
	ds_read_b128 v[20:23], v11 offset:13600
	ds_read_b128 v[24:27], v11 offset:13856
	ds_read_b128 v[28:31], v11 offset:14112
	ds_read_b128 v[32:35], v11 offset:14368
	ds_read_b128 v[36:39], v11 offset:14624
	s_waitcnt lgkmcnt(5)
	v_pk_mul_f32 v[84:85], v[0:1], v[48:49]
	v_pk_fma_f32 v[84:85], v[2:3], v[50:51], v[84:85]
	v_add_f32_e32 v86, v84, v85
	v_pk_mul_f32 v[90:91], v[0:1], v[52:53]
	v_pk_fma_f32 v[90:91], v[2:3], v[54:55], v[90:91]
	v_add_f32_dpp v88, v86, v86 quad_perm:[1,0,3,2] row_mask:0xf bank_mask:0xf bound_ctrl:1
	v_pk_mul_f32 v[92:93], v[60:61], v[64:65] op_sel_hi:[1,0]
	v_pk_fma_f32 v[92:93], v[0:1], v[44:45], v[92:93]
	v_add_f32_dpp v88, v88, v88 quad_perm:[2,3,0,1] row_mask:0xf bank_mask:0xf bound_ctrl:1
	v_pk_mul_f32 v[94:95], v[62:63], v[64:65] op_sel_hi:[1,0]
	v_pk_fma_f32 v[94:95], v[2:3], v[46:47], v[94:95]
	v_add_f32_dpp v88, v88, v88 row_half_mirror row_mask:0xf bank_mask:0xf bound_ctrl:1
	v_add_f32_e32 v77, v90, v91
	ds_read_b32 v40, v15 offset:13600
	v_add_f32_dpp v88, v88, v88 row_mirror row_mask:0xf bank_mask:0xf bound_ctrl:1
	v_pk_fma_f32 v[0:1], v[56:57], v[88:89], v[92:93] op_sel_hi:[1,0,1] neg_lo:[0,1,0] neg_hi:[0,1,0]
	v_pk_fma_f32 v[2:3], v[58:59], v[88:89], v[94:95] op_sel_hi:[1,0,1] neg_lo:[0,1,0] neg_hi:[0,1,0]
	v_cndmask_b32_e64 v114, v114, v88, s[56:57]
	ds_read_b128 v[44:47], v11 offset:14960
	ds_read_b128 v[48:51], v11 offset:15216
	ds_read_b128 v[52:55], v11 offset:15472
	ds_read_b128 v[56:59], v11 offset:15728
	ds_read_b128 v[60:63], v11 offset:15984
	s_waitcnt lgkmcnt(5)
	v_pk_mul_f32 v[84:85], v[0:1], v[24:25]
	v_pk_fma_f32 v[84:85], v[2:3], v[26:27], v[84:85]
	v_add_f32_e32 v86, v84, v85
	v_pk_mul_f32 v[90:91], v[0:1], v[28:29]
	v_pk_fma_f32 v[90:91], v[2:3], v[30:31], v[90:91]
	v_add_f32_dpp v88, v86, v86 quad_perm:[1,0,3,2] row_mask:0xf bank_mask:0xf bound_ctrl:1
	v_pk_mul_f32 v[92:93], v[36:37], v[40:41] op_sel_hi:[1,0]
	v_pk_fma_f32 v[92:93], v[0:1], v[20:21], v[92:93]
	v_add_f32_dpp v88, v88, v88 quad_perm:[2,3,0,1] row_mask:0xf bank_mask:0xf bound_ctrl:1
	v_pk_mul_f32 v[94:95], v[38:39], v[40:41] op_sel_hi:[1,0]
	v_pk_fma_f32 v[94:95], v[2:3], v[22:23], v[94:95]
	v_add_f32_dpp v88, v88, v88 row_half_mirror row_mask:0xf bank_mask:0xf bound_ctrl:1
	v_add_f32_e32 v78, v90, v91
	ds_read_b32 v64, v15 offset:14960
	v_add_f32_dpp v88, v88, v88 row_mirror row_mask:0xf bank_mask:0xf bound_ctrl:1
	v_pk_fma_f32 v[0:1], v[32:33], v[88:89], v[92:93] op_sel_hi:[1,0,1] neg_lo:[0,1,0] neg_hi:[0,1,0]
	v_pk_fma_f32 v[2:3], v[34:35], v[88:89], v[94:95] op_sel_hi:[1,0,1] neg_lo:[0,1,0] neg_hi:[0,1,0]
	v_cndmask_b32_e64 v114, v114, v88, s[58:59]
	ds_read_b128 v[20:23], v11 offset:16320
	ds_read_b128 v[24:27], v11 offset:16576
	ds_read_b128 v[28:31], v11 offset:16832
	ds_read_b128 v[32:35], v11 offset:17088
	ds_read_b128 v[36:39], v11 offset:17344
	s_waitcnt lgkmcnt(5)
	v_pk_mul_f32 v[84:85], v[0:1], v[48:49]
	v_pk_fma_f32 v[84:85], v[2:3], v[50:51], v[84:85]
	v_add_f32_e32 v86, v84, v85
	v_pk_mul_f32 v[90:91], v[0:1], v[52:53]
	v_pk_fma_f32 v[90:91], v[2:3], v[54:55], v[90:91]
	v_add_f32_dpp v88, v86, v86 quad_perm:[1,0,3,2] row_mask:0xf bank_mask:0xf bound_ctrl:1
	v_pk_mul_f32 v[92:93], v[60:61], v[64:65] op_sel_hi:[1,0]
	v_pk_fma_f32 v[92:93], v[0:1], v[44:45], v[92:93]
	v_add_f32_dpp v88, v88, v88 quad_perm:[2,3,0,1] row_mask:0xf bank_mask:0xf bound_ctrl:1
	v_pk_mul_f32 v[94:95], v[62:63], v[64:65] op_sel_hi:[1,0]
	v_pk_fma_f32 v[94:95], v[2:3], v[46:47], v[94:95]
	v_add_f32_dpp v88, v88, v88 row_half_mirror row_mask:0xf bank_mask:0xf bound_ctrl:1
	v_add_f32_e32 v79, v90, v91
	ds_read_b32 v40, v15 offset:16320
	v_add_f32_dpp v88, v88, v88 row_mirror row_mask:0xf bank_mask:0xf bound_ctrl:1
	v_pk_fma_f32 v[0:1], v[56:57], v[88:89], v[92:93] op_sel_hi:[1,0,1] neg_lo:[0,1,0] neg_hi:[0,1,0]
	v_pk_fma_f32 v[2:3], v[58:59], v[88:89], v[94:95] op_sel_hi:[1,0,1] neg_lo:[0,1,0] neg_hi:[0,1,0]
	v_cndmask_b32_e64 v114, v114, v88, s[60:61]
	ds_read_b128 v[44:47], v11 offset:17680
	ds_read_b128 v[48:51], v11 offset:17936
	ds_read_b128 v[52:55], v11 offset:18192
	ds_read_b128 v[56:59], v11 offset:18448
	ds_read_b128 v[60:63], v11 offset:18704
	s_waitcnt lgkmcnt(5)
; #define RW_PAIR(ST) do { RW_LOAD(B, (ST) + 1); RW_WAIT(A, 7); RW_STEP(A, ST); RW_LOAD(A, (ST) + 2); RW_WAIT(B, 7); RW_STEP(B, (ST) + 1); } while (0)
; __device__ __forceinline__ void scans(int l, int s, unsigned char* shm) {
;     ...
;             RW_LOAD(A, 0);
;             RW_PAIR(0); RW_PAIR(2); RW_PAIR(4); RW_PAIR(6); RW_PAIR(8); RW_PAIR(10); RW_PAIR(12);
	v_pk_mul_f32 v[84:85], v[0:1], v[24:25]
	v_pk_fma_f32 v[84:85], v[2:3], v[26:27], v[84:85]
	v_add_f32_e32 v86, v84, v85
	v_pk_mul_f32 v[90:91], v[0:1], v[28:29]
	v_pk_fma_f32 v[90:91], v[2:3], v[30:31], v[90:91]
	v_add_f32_dpp v88, v86, v86 quad_perm:[1,0,3,2] row_mask:0xf bank_mask:0xf bound_ctrl:1
	v_pk_mul_f32 v[92:93], v[36:37], v[40:41] op_sel_hi:[1,0]
	v_pk_fma_f32 v[92:93], v[0:1], v[20:21], v[92:93]
	v_add_f32_dpp v88, v88, v88 quad_perm:[2,3,0,1] row_mask:0xf bank_mask:0xf bound_ctrl:1
	v_pk_mul_f32 v[94:95], v[38:39], v[40:41] op_sel_hi:[1,0]
	v_pk_fma_f32 v[94:95], v[2:3], v[22:23], v[94:95]
	v_add_f32_dpp v88, v88, v88 row_half_mirror row_mask:0xf bank_mask:0xf bound_ctrl:1
	v_add_f32_e32 v80, v90, v91
	ds_read_b32 v64, v15 offset:17680
	v_add_f32_dpp v88, v88, v88 row_mirror row_mask:0xf bank_mask:0xf bound_ctrl:1
	v_pk_fma_f32 v[0:1], v[32:33], v[88:89], v[92:93] op_sel_hi:[1,0,1] neg_lo:[0,1,0] neg_hi:[0,1,0]
	v_pk_fma_f32 v[2:3], v[34:35], v[88:89], v[94:95] op_sel_hi:[1,0,1] neg_lo:[0,1,0] neg_hi:[0,1,0]
	v_cndmask_b32_e64 v114, v114, v88, s[62:63]
	ds_read_b128 v[20:23], v11 offset:19040
	ds_read_b128 v[24:27], v11 offset:19296
	ds_read_b128 v[28:31], v11 offset:19552
	ds_read_b128 v[32:35], v11 offset:19808
	ds_read_b128 v[36:39], v11 offset:20064
	s_waitcnt lgkmcnt(5)
	v_pk_mul_f32 v[84:85], v[0:1], v[48:49]
	v_pk_fma_f32 v[84:85], v[2:3], v[50:51], v[84:85]
	v_add_f32_e32 v86, v84, v85
	v_pk_mul_f32 v[90:91], v[0:1], v[52:53]
	v_pk_fma_f32 v[90:91], v[2:3], v[54:55], v[90:91]
	v_add_f32_dpp v88, v86, v86 quad_perm:[1,0,3,2] row_mask:0xf bank_mask:0xf bound_ctrl:1
	v_pk_mul_f32 v[92:93], v[60:61], v[64:65] op_sel_hi:[1,0]
	v_pk_fma_f32 v[92:93], v[0:1], v[44:45], v[92:93]
	v_add_f32_dpp v88, v88, v88 quad_perm:[2,3,0,1] row_mask:0xf bank_mask:0xf bound_ctrl:1
	v_pk_mul_f32 v[94:95], v[62:63], v[64:65] op_sel_hi:[1,0]
	v_pk_fma_f32 v[94:95], v[2:3], v[46:47], v[94:95]
	v_add_f32_dpp v88, v88, v88 row_half_mirror row_mask:0xf bank_mask:0xf bound_ctrl:1
	v_add_f32_e32 v81, v90, v91
	ds_read_b32 v40, v15 offset:19040
	v_add_f32_dpp v88, v88, v88 row_mirror row_mask:0xf bank_mask:0xf bound_ctrl:1
	v_pk_fma_f32 v[0:1], v[56:57], v[88:89], v[92:93] op_sel_hi:[1,0,1] neg_lo:[0,1,0] neg_hi:[0,1,0]
	v_pk_fma_f32 v[2:3], v[58:59], v[88:89], v[94:95] op_sel_hi:[1,0,1] neg_lo:[0,1,0] neg_hi:[0,1,0]
	v_cndmask_b32_e64 v114, v114, v88, s[64:65]
	ds_read_b128 v[44:47], v11 offset:20400
	ds_read_b128 v[48:51], v11 offset:20656
	ds_read_b128 v[52:55], v11 offset:20912
	ds_read_b128 v[56:59], v11 offset:21168
	ds_read_b128 v[60:63], v11 offset:21424
	s_waitcnt lgkmcnt(5)
	v_pk_mul_f32 v[84:85], v[0:1], v[24:25]
	v_pk_fma_f32 v[84:85], v[2:3], v[26:27], v[84:85]
	v_add_f32_e32 v86, v84, v85
	v_pk_mul_f32 v[90:91], v[0:1], v[28:29]
	v_pk_fma_f32 v[90:91], v[2:3], v[30:31], v[90:91]
	v_add_f32_dpp v88, v86, v86 quad_perm:[1,0,3,2] row_mask:0xf bank_mask:0xf bound_ctrl:1
	v_pk_mul_f32 v[92:93], v[36:37], v[40:41] op_sel_hi:[1,0]
	v_pk_fma_f32 v[92:93], v[0:1], v[20:21], v[92:93]
	v_add_f32_dpp v88, v88, v88 quad_perm:[2,3,0,1] row_mask:0xf bank_mask:0xf bound_ctrl:1
	v_pk_mul_f32 v[94:95], v[38:39], v[40:41] op_sel_hi:[1,0]
	v_pk_fma_f32 v[94:95], v[2:3], v[22:23], v[94:95]
	v_add_f32_dpp v88, v88, v88 row_half_mirror row_mask:0xf bank_mask:0xf bound_ctrl:1
	v_add_f32_e32 v82, v90, v91
	ds_read_b32 v64, v15 offset:20400
	v_add_f32_dpp v88, v88, v88 row_mirror row_mask:0xf bank_mask:0xf bound_ctrl:1
	v_pk_fma_f32 v[0:1], v[32:33], v[88:89], v[92:93] op_sel_hi:[1,0,1] neg_lo:[0,1,0] neg_hi:[0,1,0]
	v_pk_fma_f32 v[2:3], v[34:35], v[88:89], v[94:95] op_sel_hi:[1,0,1] neg_lo:[0,1,0] neg_hi:[0,1,0]
	v_cndmask_b32_e64 v114, v114, v88, s[66:67]
	s_waitcnt lgkmcnt(0)
; #define PG8_LAS __attribute__((address_space(3)))
; __device__ __forceinline__ bf16_t f2bf(float f) { unsigned u = __float_as_uint(f); u += 0x7FFFu + ((u >> 16) & 1u); return (bf16_t)(u >> 16); }
; #define RW_WAIT(P, N) asm volatile("s_waitcnt lgkmcnt(" #N ")" : "+v"(P##w4), "+v"(P##kk4), "+v"(P##wr4), "+v"(P##ka4), "+v"(P##kp4), "+v"(P##v), "+v"(P##cc))
; #define RW_PAIR(ST) do { RW_LOAD(B, (ST) + 1); RW_WAIT(A, 7); RW_STEP(A, ST); RW_LOAD(A, (ST) + 2); RW_WAIT(B, 7); RW_STEP(B, (ST) + 1); } while (0)
; __device__ __forceinline__ void scans(int l, int s, unsigned char* shm) {
;     ...
;             if (cidx > 0) { const int st = tid >> 4, r = tid & 15; Y[(size_t)(b_r * 2048 + (cidx - 1) * CS + st) * 512 + h_r * 64 + rbase + r] = f2bf(yl[((cidx - 1) & 1) * (CS * 16) + tid]); }
;             const float* bp = rbuf + (cidx & 1) * (CS * RST); float* ylw = yl + (cidx & 1) * (CS * 16);
;             const unsigned ab = (unsigned)(size_t)(PG8_LAS const float*)bp;
;             const unsigned a_col = ab + col4 * 4, a_row = ab + 1280 + loc * 4, a_cc = ab + 1344;
;             f32x4 Aw4, Akk4, Awr4, Aka4, Akp4, Bw4, Bkk4, Bwr4, Bka4, Bkp4; float Av, Bv; f32x2 Acc, Bcc;
;             float ykeep = 0.f;
;     ...
;             RW_LOAD(A, 0);
;             RW_PAIR(0); RW_PAIR(2); RW_PAIR(4); RW_PAIR(6); RW_PAIR(8); RW_PAIR(10); RW_PAIR(12);
;             RW_LOAD(B, 15); RW_WAIT(A, 7); RW_STEP(A, 14); RW_WAIT(B, 0); RW_STEP(B, 15);
;     ...
;             ylw[(lane & 15) * 16 + loc] = ykeep;
;             __syncthreads();
	v_pk_mul_f32 v[84:85], v[0:1], v[48:49]
	v_pk_fma_f32 v[84:85], v[2:3], v[50:51], v[84:85]
	v_add_f32_e32 v86, v84, v85
	v_pk_mul_f32 v[90:91], v[0:1], v[52:53]
	v_pk_fma_f32 v[90:91], v[2:3], v[54:55], v[90:91]
	v_add_f32_dpp v88, v86, v86 quad_perm:[1,0,3,2] row_mask:0xf bank_mask:0xf bound_ctrl:1
	v_pk_mul_f32 v[92:93], v[60:61], v[64:65] op_sel_hi:[1,0]
	v_pk_fma_f32 v[92:93], v[0:1], v[44:45], v[92:93]
	v_add_f32_dpp v88, v88, v88 quad_perm:[2,3,0,1] row_mask:0xf bank_mask:0xf bound_ctrl:1
	v_pk_mul_f32 v[94:95], v[62:63], v[64:65] op_sel_hi:[1,0]
	v_pk_fma_f32 v[94:95], v[2:3], v[46:47], v[94:95]
	v_add_f32_dpp v88, v88, v88 row_half_mirror row_mask:0xf bank_mask:0xf bound_ctrl:1
	v_add_f32_e32 v83, v90, v91
	v_add_u32_e32 v112, v15, v125
	v_add_f32_dpp v88, v88, v88 row_mirror row_mask:0xf bank_mask:0xf bound_ctrl:1
	v_pk_fma_f32 v[0:1], v[56:57], v[88:89], v[92:93] op_sel_hi:[1,0,1] neg_lo:[0,1,0] neg_hi:[0,1,0]
	v_pk_fma_f32 v[2:3], v[58:59], v[88:89], v[94:95] op_sel_hi:[1,0,1] neg_lo:[0,1,0] neg_hi:[0,1,0]
	v_cndmask_b32_e64 v114, v114, v88, s[68:69]
	v_add_u32_e32 v113, v16, v125
	ds_read_b32 v110, v112
	ds_read_b64 v[116:117], v113
	v_and_b32_e32 v118, 1, v4
	v_cmp_ne_u32_e32 vcc, 0, v118
	v_add_f32_dpp v68, v68, v68 row_ror:8 row_mask:0xf bank_mask:0x3
	v_add_f32_dpp v68, v76, v76 row_ror:8 row_mask:0xf bank_mask:0xc
	v_add_f32_dpp v69, v69, v69 row_ror:8 row_mask:0xf bank_mask:0x3
	v_add_f32_dpp v69, v77, v77 row_ror:8 row_mask:0xf bank_mask:0xc
	v_add_f32_dpp v70, v70, v70 row_ror:8 row_mask:0xf bank_mask:0x3
	v_add_f32_dpp v70, v78, v78 row_ror:8 row_mask:0xf bank_mask:0xc
	v_add_f32_dpp v71, v71, v71 row_ror:8 row_mask:0xf bank_mask:0x3
	v_add_f32_dpp v71, v79, v79 row_ror:8 row_mask:0xf bank_mask:0xc
	v_add_f32_dpp v72, v72, v72 row_ror:8 row_mask:0xf bank_mask:0x3
	v_add_f32_dpp v72, v80, v80 row_ror:8 row_mask:0xf bank_mask:0xc
	v_add_f32_dpp v73, v73, v73 row_ror:8 row_mask:0xf bank_mask:0x3
	v_add_f32_dpp v73, v81, v81 row_ror:8 row_mask:0xf bank_mask:0xc
	v_add_f32_dpp v74, v74, v74 row_ror:8 row_mask:0xf bank_mask:0x3
	v_add_f32_dpp v74, v82, v82 row_ror:8 row_mask:0xf bank_mask:0xc
	v_add_f32_dpp v75, v75, v75 row_ror:8 row_mask:0xf bank_mask:0x3
	v_add_f32_dpp v75, v83, v83 row_ror:8 row_mask:0xf bank_mask:0xc
	v_add_f32_dpp v68, v68, v68 row_half_mirror row_mask:0xf bank_mask:0x5
	v_add_f32_dpp v68, v72, v72 row_half_mirror row_mask:0xf bank_mask:0xa
	v_add_f32_dpp v69, v69, v69 row_half_mirror row_mask:0xf bank_mask:0x5
	v_add_f32_dpp v69, v73, v73 row_half_mirror row_mask:0xf bank_mask:0xa
	v_add_f32_dpp v70, v70, v70 row_half_mirror row_mask:0xf bank_mask:0x5
	v_add_f32_dpp v70, v74, v74 row_half_mirror row_mask:0xf bank_mask:0xa
	v_add_f32_dpp v71, v71, v71 row_half_mirror row_mask:0xf bank_mask:0x5
	v_add_f32_dpp v71, v75, v75 row_half_mirror row_mask:0xf bank_mask:0xa
	v_cndmask_b32_e64 v100, v70, v68, s[100:101]
	v_cndmask_b32_e64 v101, v71, v69, s[100:101]
	v_cndmask_b32_e64 v102, v68, v70, s[100:101]
	v_cndmask_b32_e64 v103, v69, v71, s[100:101]
	v_add_f32_dpp v104, v100, v102 quad_perm:[2,3,0,1] row_mask:0xf bank_mask:0xf bound_ctrl:1
	v_add_f32_dpp v105, v101, v103 quad_perm:[2,3,0,1] row_mask:0xf bank_mask:0xf bound_ctrl:1
	v_lshl_add_u32 v17, s20, 10, v14
	v_cndmask_b32_e32 v106, v105, v104, vcc
	v_cndmask_b32_e32 v107, v104, v105, vcc
	s_add_i32 s16, s16, 1
	s_addk_i32 s17, 0x100
	v_add_u32_e32 v10, 16, v10
	v_add_f32_dpp v108, v106, v107 quad_perm:[1,0,3,2] row_mask:0xf bank_mask:0xf bound_ctrl:1
	s_waitcnt lgkmcnt(0)
	v_fmac_f32_e32 v108, v110, v117
	v_fma_f32 v108, -v116, v114, v108
	ds_write_b32 v17, v108 offset:43520
	s_cmpk_eq_i32 s17, 0x7f00
	s_waitcnt lgkmcnt(0)
	s_barrier
	s_cbranch_scc1 .LBB0_761
.LBB0_759:
	s_cmp_eq_u32 s16, 0
	s_cbranch_scc1 .LBB0_758
	s_and_b32 s20, s17, 0x100
	v_lshl_add_u32 v119, s20, 2, v5
	ds_read_b32 v119, v119 offset:43520
	v_ashrrev_i32_e32 v11, 31, v10
	v_lshlrev_b64 v[120:121], 10, v[10:11]
	v_lshl_add_u64 v[120:121], v[8:9], 0, v[120:121]
	s_branch .LBB0_758
